# stack9 plus fp8 row-scale absmax wave reduction via DPP and permlane swaps instead of six LDS bpermute round trips
# speedup vs baseline: 1.0023x; 1.0023x over previous
; DI void fp8_rows(const float* __restrict__ src, unsigned char* __restrict__ dst, float* __restrict__ rs, int nrows) {
;   const int lane = threadIdx.x & 63, w = threadIdx.x >> 6;
;   for (int row = blockIdx.x * 4 + w; row < nrows; row += gridDim.x * 4) {
;     float4 v[4];
;     float am = 0.f;
; #pragma unroll
;     for (int i = 0; i < 4; ++i) {
;       v[i] = *(const float4*)(src + (size_t)row * 1024 + 4 * lane + 256 * i);
;       am = fmaxf(am, fmaxf(fmaxf(fabsf(v[i].x), fabsf(v[i].y)), fmaxf(fabsf(v[i].z), fabsf(v[i].w))));
;     }
;     am = fmaxf(am, __shfl_xor(am, 32)); am = fmaxf(am, __shfl_xor(am, 16)); am = fmaxf(am, __shfl_xor(am, 8));
;     am = fmaxf(am, __shfl_xor(am, 4)); am = fmaxf(am, __shfl_xor(am, 2)); am = fmaxf(am, __shfl_xor(am, 1));
;     const float sc = am > 0.f ? 440.f / am : 1.f;
;     if (lane == 0) rs[row] = am > 0.f ? am / 440.f : 1.f;
.LBB0_408:
	v_ashrrev_i32_e32 v19, 31, v18
	v_lshlrev_b64 v[2:3], 12, v[18:19]
	v_lshl_add_u64 v[2:3], v[166:167], 0, v[2:3]
	global_load_dwordx4 v[14:17], v[2:3], off
	global_load_dwordx4 v[10:13], v[2:3], off offset:1024
	global_load_dwordx4 v[6:9], v[2:3], off offset:2048
	s_nop 0
	global_load_dwordx4 v[2:5], v[2:3], off offset:3072
	s_waitcnt vmcnt(3)
	v_max_f32_e64 v25, |v17|, |v17|
	v_max_f32_e64 v26, |v16|, |v16|
	s_waitcnt vmcnt(2)
	v_max_f32_e64 v27, |v13|, |v13|
	v_max_f32_e64 v28, |v12|, |v12|
	s_waitcnt vmcnt(1)
	v_max_f32_e64 v29, |v9|, |v9|
	v_max_f32_e64 v30, |v8|, |v8|
	s_waitcnt vmcnt(0)
	v_max_f32_e64 v31, |v5|, |v5|
	v_max_f32_e64 v32, |v4|, |v4|
	v_max_f32_e32 v25, v26, v25
	v_max_f32_e32 v26, v28, v27
	v_max_f32_e32 v27, v30, v29
	v_max_f32_e32 v28, v32, v31
	v_max3_f32 v25, |v14|, |v15|, v25
	v_max3_f32 v26, |v10|, |v11|, v26
	v_max3_f32 v27, |v6|, |v7|, v27
	v_max3_f32 v25, v25, 0, v26
	v_max3_f32 v26, |v2|, |v3|, v28
	v_max3_f32 v25, v25, v27, v26
	s_nop 1
	v_max_f32_dpp v25, v25, v25 quad_perm:[1,0,3,2] row_mask:0xf bank_mask:0xf
	s_nop 1
	v_max_f32_dpp v25, v25, v25 quad_perm:[2,3,0,1] row_mask:0xf bank_mask:0xf
	s_nop 1
	v_max_f32_dpp v25, v25, v25 row_half_mirror row_mask:0xf bank_mask:0xf
	s_nop 1
	v_max_f32_dpp v25, v25, v25 row_mirror row_mask:0xf bank_mask:0xf
	v_mov_b32_e32 v26, v25
	s_nop 1
	v_permlane16_swap_b32_e32 v25, v26
	v_max_f32_e32 v25, v25, v26
	v_mov_b32_e32 v26, v25
	s_nop 1
	v_permlane32_swap_b32_e32 v25, v26
	v_max_f32_e32 v25, v25, v26
	v_cmp_lt_f32_e64 s[12:13], 0, v25
	s_and_saveexec_b64 s[54:55], s[10:11]
	s_cbranch_execz .LBB0_407
	v_div_scale_f32 v26, s[6:7], s5, s5, v25
	v_rcp_f32_e32 v27, v26
	v_div_scale_f32 v28, vcc, v25, s5, v25
	v_fma_f32 v29, -v26, v27, 1.0
	v_fmac_f32_e32 v27, v29, v27
	v_mul_f32_e32 v29, v28, v27
	v_fma_f32 v30, -v26, v29, v28
	v_fmac_f32_e32 v29, v30, v27
	v_fma_f32 v26, -v26, v29, v28
	v_div_fmas_f32 v26, v26, v27, v29
	v_div_fixup_f32 v26, v26, s5, v25
	v_cndmask_b32_e64 v28, 1.0, v26, s[12:13]
	v_lshl_add_u64 v[26:27], v[18:19], 2, s[34:35]
	global_store_dword v[26:27], v28, off
	s_branch .LBB0_407

; DI void fp8_rows(const float* __restrict__ src, unsigned char* __restrict__ dst, float* __restrict__ rs, int nrows) {
;   const int lane = threadIdx.x & 63, w = threadIdx.x >> 6;
;   for (int row = blockIdx.x * 4 + w; row < nrows; row += gridDim.x * 4) {
;     float4 v[4];
;     float am = 0.f;
; #pragma unroll
;     for (int i = 0; i < 4; ++i) {
;       v[i] = *(const float4*)(src + (size_t)row * 1024 + 4 * lane + 256 * i);
;       am = fmaxf(am, fmaxf(fmaxf(fabsf(v[i].x), fabsf(v[i].y)), fmaxf(fabsf(v[i].z), fabsf(v[i].w))));
;     }
;     am = fmaxf(am, __shfl_xor(am, 32)); am = fmaxf(am, __shfl_xor(am, 16)); am = fmaxf(am, __shfl_xor(am, 8));
;     am = fmaxf(am, __shfl_xor(am, 4)); am = fmaxf(am, __shfl_xor(am, 2)); am = fmaxf(am, __shfl_xor(am, 1));
;     const float sc = am > 0.f ? 440.f / am : 1.f;
;     if (lane == 0) rs[row] = am > 0.f ? am / 440.f : 1.f;
.LBB0_412:
	v_ashrrev_i32_e32 v19, 31, v18
	v_lshlrev_b64 v[2:3], 12, v[18:19]
	v_lshl_add_u64 v[2:3], v[168:169], 0, v[2:3]
	global_load_dwordx4 v[14:17], v[2:3], off
	global_load_dwordx4 v[10:13], v[2:3], off offset:1024
	global_load_dwordx4 v[6:9], v[2:3], off offset:2048
	s_nop 0
	global_load_dwordx4 v[2:5], v[2:3], off offset:3072
	s_waitcnt vmcnt(3)
	v_max_f32_e64 v25, |v17|, |v17|
	v_max_f32_e64 v26, |v16|, |v16|
	s_waitcnt vmcnt(2)
	v_max_f32_e64 v27, |v13|, |v13|
	v_max_f32_e64 v28, |v12|, |v12|
	s_waitcnt vmcnt(1)
	v_max_f32_e64 v29, |v9|, |v9|
	v_max_f32_e64 v30, |v8|, |v8|
	s_waitcnt vmcnt(0)
	v_max_f32_e64 v31, |v5|, |v5|
	v_max_f32_e64 v32, |v4|, |v4|
	v_max_f32_e32 v25, v26, v25
	v_max_f32_e32 v26, v28, v27
	v_max_f32_e32 v27, v30, v29
	v_max_f32_e32 v28, v32, v31
	v_max3_f32 v25, |v14|, |v15|, v25
	v_max3_f32 v26, |v10|, |v11|, v26
	v_max3_f32 v27, |v6|, |v7|, v27
	v_max3_f32 v25, v25, 0, v26
	v_max3_f32 v26, |v2|, |v3|, v28
	v_max3_f32 v25, v25, v27, v26
	s_nop 1
	v_max_f32_dpp v25, v25, v25 quad_perm:[1,0,3,2] row_mask:0xf bank_mask:0xf
	s_nop 1
	v_max_f32_dpp v25, v25, v25 quad_perm:[2,3,0,1] row_mask:0xf bank_mask:0xf
	s_nop 1
	v_max_f32_dpp v25, v25, v25 row_half_mirror row_mask:0xf bank_mask:0xf
	s_nop 1
	v_max_f32_dpp v25, v25, v25 row_mirror row_mask:0xf bank_mask:0xf
	v_mov_b32_e32 v26, v25
	s_nop 1
	v_permlane16_swap_b32_e32 v25, v26
	v_max_f32_e32 v25, v25, v26
	v_mov_b32_e32 v26, v25
	s_nop 1
	v_permlane32_swap_b32_e32 v25, v26
	v_max_f32_e32 v25, v25, v26
	v_cmp_lt_f32_e64 s[12:13], 0, v25
	s_and_saveexec_b64 s[54:55], s[10:11]
	s_cbranch_execz .LBB0_411
	v_div_scale_f32 v26, s[6:7], s5, s5, v25
	v_rcp_f32_e32 v27, v26
	v_div_scale_f32 v28, vcc, v25, s5, v25
	v_fma_f32 v29, -v26, v27, 1.0
	v_fmac_f32_e32 v27, v29, v27
	v_mul_f32_e32 v29, v28, v27
	v_fma_f32 v30, -v26, v29, v28
	v_fmac_f32_e32 v29, v30, v27
	v_fma_f32 v26, -v26, v29, v28
	v_div_fmas_f32 v26, v26, v27, v29
	v_div_fixup_f32 v26, v26, s5, v25
	v_cndmask_b32_e64 v28, 1.0, v26, s[12:13]
	v_lshl_add_u64 v[26:27], v[18:19], 2, s[42:43]
	global_store_dword v[26:27], v28, off
	s_branch .LBB0_411

; DI void fp8_rows(const float* __restrict__ src, unsigned char* __restrict__ dst, float* __restrict__ rs, int nrows) {
;   const int lane = threadIdx.x & 63, w = threadIdx.x >> 6;
;   for (int row = blockIdx.x * 4 + w; row < nrows; row += gridDim.x * 4) {
;     float4 v[4];
;     float am = 0.f;
; #pragma unroll
;     for (int i = 0; i < 4; ++i) {
;       v[i] = *(const float4*)(src + (size_t)row * 1024 + 4 * lane + 256 * i);
;       am = fmaxf(am, fmaxf(fmaxf(fabsf(v[i].x), fabsf(v[i].y)), fmaxf(fabsf(v[i].z), fabsf(v[i].w))));
;     }
;     am = fmaxf(am, __shfl_xor(am, 32)); am = fmaxf(am, __shfl_xor(am, 16)); am = fmaxf(am, __shfl_xor(am, 8));
;     am = fmaxf(am, __shfl_xor(am, 4)); am = fmaxf(am, __shfl_xor(am, 2)); am = fmaxf(am, __shfl_xor(am, 1));
;     const float sc = am > 0.f ? 440.f / am : 1.f;
;     if (lane == 0) rs[row] = am > 0.f ? am / 440.f : 1.f;
.LBB0_598:
	v_ashrrev_i32_e32 v17, 31, v16
	v_lshlrev_b64 v[0:1], 12, v[16:17]
	v_lshl_add_u64 v[12:13], v[130:131], 0, v[0:1]
	global_load_dwordx4 v[0:3], v[12:13], off
	global_load_dwordx4 v[4:7], v[12:13], off offset:1024
	global_load_dwordx4 v[8:11], v[12:13], off offset:2048
	s_nop 0
	global_load_dwordx4 v[12:15], v[12:13], off offset:3072
	s_waitcnt vmcnt(3)
	v_max_f32_e64 v24, |v3|, |v3|
	v_max_f32_e64 v25, |v2|, |v2|
	s_waitcnt vmcnt(2)
	v_max_f32_e64 v26, |v7|, |v7|
	v_max_f32_e64 v27, |v6|, |v6|
	s_waitcnt vmcnt(1)
	v_max_f32_e64 v28, |v11|, |v11|
	v_max_f32_e64 v29, |v10|, |v10|
	s_waitcnt vmcnt(0)
	v_max_f32_e64 v30, |v15|, |v15|
	v_max_f32_e64 v31, |v14|, |v14|
	v_max_f32_e32 v24, v25, v24
	v_max_f32_e32 v25, v27, v26
	v_max_f32_e32 v26, v29, v28
	v_max_f32_e32 v27, v31, v30
	v_max3_f32 v24, |v0|, |v1|, v24
	v_max3_f32 v25, |v4|, |v5|, v25
	v_max3_f32 v26, |v8|, |v9|, v26
	v_max3_f32 v24, v24, 0, v25
	v_max3_f32 v25, |v12|, |v13|, v27
	v_max3_f32 v24, v24, v26, v25
	s_nop 1
	v_max_f32_dpp v24, v24, v24 quad_perm:[1,0,3,2] row_mask:0xf bank_mask:0xf
	s_nop 1
	v_max_f32_dpp v24, v24, v24 quad_perm:[2,3,0,1] row_mask:0xf bank_mask:0xf
	s_nop 1
	v_max_f32_dpp v24, v24, v24 row_half_mirror row_mask:0xf bank_mask:0xf
	s_nop 1
	v_max_f32_dpp v24, v24, v24 row_mirror row_mask:0xf bank_mask:0xf
	v_mov_b32_e32 v25, v24
	s_nop 1
	v_permlane16_swap_b32_e32 v24, v25
	v_max_f32_e32 v24, v24, v25
	v_mov_b32_e32 v25, v24
	s_nop 1
	v_permlane32_swap_b32_e32 v24, v25
	v_max_f32_e32 v24, v24, v25
	v_cmp_lt_f32_e64 s[12:13], 0, v24
	s_and_saveexec_b64 s[56:57], s[10:11]
	s_cbranch_execz .LBB0_597
	v_div_scale_f32 v25, s[4:5], s64, s64, v24
	v_rcp_f32_e32 v26, v25
	v_div_scale_f32 v27, vcc, v24, s64, v24
	v_fma_f32 v28, -v25, v26, 1.0
	v_fmac_f32_e32 v26, v28, v26
	v_mul_f32_e32 v28, v27, v26
	v_fma_f32 v29, -v25, v28, v27
	v_fmac_f32_e32 v28, v29, v26
	v_fma_f32 v25, -v25, v28, v27
	v_div_fmas_f32 v25, v25, v26, v28
	v_div_fixup_f32 v25, v25, s64, v24
	v_cndmask_b32_e64 v25, 1.0, v25, s[12:13]
	v_lshl_add_u64 v[26:27], v[16:17], 2, s[52:53]
	global_store_dword v[26:27], v25, off
	s_branch .LBB0_597

; DI void fp8_rows(const float* __restrict__ src, unsigned char* __restrict__ dst, float* __restrict__ rs, int nrows) {
;   const int lane = threadIdx.x & 63, w = threadIdx.x >> 6;
;   for (int row = blockIdx.x * 4 + w; row < nrows; row += gridDim.x * 4) {
;     float4 v[4];
;     float am = 0.f;
; #pragma unroll
;     for (int i = 0; i < 4; ++i) {
;       v[i] = *(const float4*)(src + (size_t)row * 1024 + 4 * lane + 256 * i);
;       am = fmaxf(am, fmaxf(fmaxf(fabsf(v[i].x), fabsf(v[i].y)), fmaxf(fabsf(v[i].z), fabsf(v[i].w))));
;     }
;     am = fmaxf(am, __shfl_xor(am, 32)); am = fmaxf(am, __shfl_xor(am, 16)); am = fmaxf(am, __shfl_xor(am, 8));
;     am = fmaxf(am, __shfl_xor(am, 4)); am = fmaxf(am, __shfl_xor(am, 2)); am = fmaxf(am, __shfl_xor(am, 1));
;     const float sc = am > 0.f ? 440.f / am : 1.f;
;     if (lane == 0) rs[row] = am > 0.f ? am / 440.f : 1.f;
.LBB0_602:
	v_ashrrev_i32_e32 v17, 31, v16
	v_lshlrev_b64 v[0:1], 12, v[16:17]
	v_lshl_add_u64 v[12:13], v[134:135], 0, v[0:1]
	global_load_dwordx4 v[0:3], v[12:13], off
	global_load_dwordx4 v[4:7], v[12:13], off offset:1024
	global_load_dwordx4 v[8:11], v[12:13], off offset:2048
	s_nop 0
	global_load_dwordx4 v[12:15], v[12:13], off offset:3072
	s_waitcnt vmcnt(3)
	v_max_f32_e64 v24, |v3|, |v3|
	v_max_f32_e64 v25, |v2|, |v2|
	s_waitcnt vmcnt(2)
	v_max_f32_e64 v26, |v7|, |v7|
	v_max_f32_e64 v27, |v6|, |v6|
	s_waitcnt vmcnt(1)
	v_max_f32_e64 v28, |v11|, |v11|
	v_max_f32_e64 v29, |v10|, |v10|
	s_waitcnt vmcnt(0)
	v_max_f32_e64 v30, |v15|, |v15|
	v_max_f32_e64 v31, |v14|, |v14|
	v_max_f32_e32 v24, v25, v24
	v_max_f32_e32 v25, v27, v26
	v_max_f32_e32 v26, v29, v28
	v_max_f32_e32 v27, v31, v30
	v_max3_f32 v24, |v0|, |v1|, v24
	v_max3_f32 v25, |v4|, |v5|, v25
	v_max3_f32 v26, |v8|, |v9|, v26
	v_max3_f32 v24, v24, 0, v25
	v_max3_f32 v25, |v12|, |v13|, v27
	v_max3_f32 v24, v24, v26, v25
	s_nop 1
	v_max_f32_dpp v24, v24, v24 quad_perm:[1,0,3,2] row_mask:0xf bank_mask:0xf
	s_nop 1
	v_max_f32_dpp v24, v24, v24 quad_perm:[2,3,0,1] row_mask:0xf bank_mask:0xf
	s_nop 1
	v_max_f32_dpp v24, v24, v24 row_half_mirror row_mask:0xf bank_mask:0xf
	s_nop 1
	v_max_f32_dpp v24, v24, v24 row_mirror row_mask:0xf bank_mask:0xf
	v_mov_b32_e32 v25, v24
	s_nop 1
	v_permlane16_swap_b32_e32 v24, v25
	v_max_f32_e32 v24, v24, v25
	v_mov_b32_e32 v25, v24
	s_nop 1
	v_permlane32_swap_b32_e32 v24, v25
	v_max_f32_e32 v24, v24, v25
	v_cmp_lt_f32_e64 s[12:13], 0, v24
	s_and_saveexec_b64 s[56:57], s[10:11]
	s_cbranch_execz .LBB0_601
	v_div_scale_f32 v25, s[4:5], s64, s64, v24
	v_rcp_f32_e32 v26, v25
	v_div_scale_f32 v27, vcc, v24, s64, v24
	v_fma_f32 v28, -v25, v26, 1.0
	v_fmac_f32_e32 v26, v28, v26
	v_mul_f32_e32 v28, v27, v26
	v_fma_f32 v29, -v25, v28, v27
	v_fmac_f32_e32 v28, v29, v26
	v_fma_f32 v25, -v25, v28, v27
	v_div_fmas_f32 v25, v25, v26, v28
	v_div_fixup_f32 v25, v25, s64, v24
	v_cndmask_b32_e64 v25, 1.0, v25, s[12:13]
	v_lshl_add_u64 v[26:27], v[16:17], 2, s[16:17]
	global_store_dword v[26:27], v25, off
	s_branch .LBB0_601
